# idsw12b
# speedup vs baseline: 1.0129x; 1.0015x over previous
.LBB0_622:
	s_mov_b32 s9, s18
	s_cmp_lt_i32 s22, 8
	s_cselect_b32 s17, s22, s9
	s_waitcnt vmcnt(1)
	ds_swizzle_b32 v140, v250 offset:24
	ds_swizzle_b32 v141, v251 offset:24
	ds_swizzle_b32 v142, v250 offset:56
	ds_swizzle_b32 v143, v251 offset:56
	ds_swizzle_b32 v132, v250 offset:88
	ds_swizzle_b32 v133, v251 offset:88
	ds_swizzle_b32 v134, v250 offset:120
	ds_swizzle_b32 v135, v251 offset:120
	ds_swizzle_b32 v108, v250 offset:152
	ds_swizzle_b32 v109, v251 offset:152
	ds_swizzle_b32 v110, v250 offset:184
	ds_swizzle_b32 v111, v251 offset:184
	ds_swizzle_b32 v100, v250 offset:216
	ds_swizzle_b32 v101, v251 offset:216
	ds_swizzle_b32 v102, v250 offset:248
	ds_swizzle_b32 v103, v251 offset:248
	s_waitcnt lgkmcnt(0)
	s_nop 0
	v_lshl_or_b32 v80, s17, 21, v196
	s_waitcnt vmcnt(1)
	v_lshl_add_u32 v81, v140, 7, v80
	v_lshl_add_u32 v82, v141, 7, v80
	s_mov_b32 s16, s23
	global_load_dwordx4 v[168:171], v81, s[4:5]
	global_load_dwordx4 v[164:167], v82, s[4:5]
	v_lshl_add_u32 v81, v142, 7, v80
	v_lshl_add_u32 v82, v143, 7, v80
	global_load_dwordx4 v[160:163], v81, s[4:5]
	global_load_dwordx4 v[156:159], v82, s[4:5]
	v_lshl_add_u32 v81, v132, 7, v80
	v_lshl_add_u32 v82, v133, 7, v80
	s_cselect_b32 s20, s8, s16
	global_load_dwordx4 v[152:155], v81, s[4:5]
	global_load_dwordx4 v[144:147], v82, s[4:5]
	v_lshl_add_u32 v81, v134, 7, v80
	v_lshl_add_u32 v82, v135, 7, v80
	s_ashr_i32 s21, s20, 31
	global_load_dwordx4 v[136:139], v81, s[4:5]
	global_load_dwordx4 v[128:131], v82, s[4:5]
	v_lshl_add_u32 v81, v108, 7, v80
	v_lshl_add_u32 v82, v109, 7, v80
	s_lshl_b64 s[20:21], s[20:21], 9
	global_load_dwordx4 v[124:127], v81, s[4:5]
	global_load_dwordx4 v[120:123], v82, s[4:5]
	v_lshl_add_u32 v81, v110, 7, v80
	v_lshl_add_u32 v82, v111, 7, v80
	s_cmp_lt_i32 s27, 8
	global_load_dwordx4 v[112:115], v81, s[4:5]
	global_load_dwordx4 v[104:107], v82, s[4:5]
	v_lshl_add_u32 v81, v100, 7, v80
	v_lshl_add_u32 v82, v101, 7, v80
	v_lshl_add_u64 v[100:101], v[244:245], 0, s[20:21]
	s_cselect_b64 s[20:21], -1, 0
	s_and_b64 s[24:25], s[20:21], exec
	s_cselect_b32 s24, s26, s16
	s_ashr_i32 s25, s24, 31
	global_load_dwordx4 v[96:99], v81, s[4:5]
	global_load_dwordx4 v[92:95], v82, s[4:5]
	v_lshl_add_u32 v81, v102, 7, v80
	v_lshl_add_u32 v80, v103, 7, v80
	s_lshl_b64 s[24:25], s[24:25], 9
	global_load_dwordx4 v[88:91], v81, s[4:5]
	s_nop 0
	global_load_dwordx4 v[80:83], v80, s[4:5]
	s_nop 0
	ds_swizzle_b32 v60, v248 offset:24
	ds_swizzle_b32 v61, v249 offset:24
	ds_swizzle_b32 v62, v248 offset:56
	ds_swizzle_b32 v63, v249 offset:56
	ds_swizzle_b32 v36, v248 offset:88
	ds_swizzle_b32 v37, v249 offset:88
	ds_swizzle_b32 v38, v248 offset:120
	ds_swizzle_b32 v39, v249 offset:120
	ds_swizzle_b32 v12, v248 offset:152
	ds_swizzle_b32 v13, v249 offset:152
	ds_swizzle_b32 v14, v248 offset:184
	ds_swizzle_b32 v15, v249 offset:184
	ds_swizzle_b32 v0, v248 offset:216
	ds_swizzle_b32 v1, v249 offset:216
	ds_swizzle_b32 v2, v248 offset:248
	ds_swizzle_b32 v3, v249 offset:248
	global_load_dwordx2 v[248:249], v[100:101], off
	v_lshl_add_u64 v[100:101], v[246:247], 0, s[24:25]
	global_load_dwordx2 v[250:251], v[100:101], off
	s_waitcnt lgkmcnt(0)
	s_nop 0
	v_cvt_scalef32_pk_f16_fp8 v100, v76, 1.0
	v_cvt_scalef32_pk_f16_fp8 v76, v76, 1.0 op_sel:[1,0,0]
	v_cvt_scalef32_pk_f16_fp8 v101, v77, 1.0
	v_cvt_scalef32_pk_f16_fp8 v77, v77, 1.0 op_sel:[1,0,0]
	v_cvt_scalef32_pk_f16_fp8 v102, v78, 1.0
	v_cvt_scalef32_pk_f16_fp8 v78, v78, 1.0 op_sel:[1,0,0]
	v_cvt_scalef32_pk_f16_fp8 v103, v79, 1.0
	v_cvt_scalef32_pk_f16_fp8 v79, v79, 1.0 op_sel:[1,0,0]
	v_pk_fma_f16 v100, v100, v60, 0
	v_pk_fma_f16 v76, v76, v60, 0
	v_pk_fma_f16 v101, v101, v60, 0
	v_pk_fma_f16 v77, v77, v60, 0
	v_pk_fma_f16 v102, v102, v60, 0
	v_pk_fma_f16 v78, v78, v60, 0
	v_pk_fma_f16 v103, v103, v60, 0
	v_pk_fma_f16 v60, v79, v60, 0
	v_cvt_scalef32_pk_f16_fp8 v79, v72, 1.0
	v_cvt_scalef32_pk_f16_fp8 v72, v72, 1.0 op_sel:[1,0,0]
	v_pk_fma_f16 v72, v72, v61, v76
	v_cvt_scalef32_pk_f16_fp8 v76, v73, 1.0
	v_cvt_scalef32_pk_f16_fp8 v73, v73, 1.0 op_sel:[1,0,0]
	v_pk_fma_f16 v73, v73, v61, v77
	v_cvt_scalef32_pk_f16_fp8 v77, v74, 1.0
	v_cvt_scalef32_pk_f16_fp8 v74, v74, 1.0 op_sel:[1,0,0]
	v_pk_fma_f16 v74, v74, v61, v78
	v_cvt_scalef32_pk_f16_fp8 v78, v75, 1.0
	v_cvt_scalef32_pk_f16_fp8 v75, v75, 1.0 op_sel:[1,0,0]
	v_pk_fma_f16 v79, v79, v61, v100
	v_pk_fma_f16 v76, v76, v61, v101
	v_pk_fma_f16 v77, v77, v61, v102
	v_pk_fma_f16 v78, v78, v61, v103
	v_pk_fma_f16 v60, v75, v61, v60
	v_cvt_scalef32_pk_f16_fp8 v61, v68, 1.0
	v_cvt_scalef32_pk_f16_fp8 v68, v68, 1.0 op_sel:[1,0,0]
	v_pk_fma_f16 v68, v68, v62, v72
	v_cvt_scalef32_pk_f16_fp8 v72, v69, 1.0
	v_cvt_scalef32_pk_f16_fp8 v69, v69, 1.0 op_sel:[1,0,0]
	v_pk_fma_f16 v69, v69, v62, v73
	v_cvt_scalef32_pk_f16_fp8 v73, v70, 1.0
	v_cvt_scalef32_pk_f16_fp8 v70, v70, 1.0 op_sel:[1,0,0]
	v_pk_fma_f16 v70, v70, v62, v74
	v_cvt_scalef32_pk_f16_fp8 v74, v71, 1.0
	v_cvt_scalef32_pk_f16_fp8 v71, v71, 1.0 op_sel:[1,0,0]
	v_pk_fma_f16 v61, v61, v62, v79
	v_pk_fma_f16 v72, v72, v62, v76
	v_pk_fma_f16 v73, v73, v62, v77
	v_pk_fma_f16 v74, v74, v62, v78
	v_pk_fma_f16 v60, v71, v62, v60
	v_cvt_scalef32_pk_f16_fp8 v62, v64, 1.0
	v_pk_fma_f16 v61, v62, v63, v61
	v_cvt_scalef32_pk_f16_fp8 v62, v64, 1.0 op_sel:[1,0,0]
	v_cvt_scalef32_pk_f16_fp8 v64, v65, 1.0
	v_cvt_scalef32_pk_f16_fp8 v65, v65, 1.0 op_sel:[1,0,0]
	v_pk_fma_f16 v62, v62, v63, v68
	v_pk_fma_f16 v65, v65, v63, v69
	v_cvt_scalef32_pk_f16_fp8 v68, v66, 1.0
	v_cvt_scalef32_pk_f16_fp8 v66, v66, 1.0 op_sel:[1,0,0]
	v_cvt_scalef32_pk_f16_fp8 v69, v67, 1.0
	v_cvt_scalef32_pk_f16_fp8 v67, v67, 1.0 op_sel:[1,0,0]
	v_pk_fma_f16 v64, v64, v63, v72
	v_pk_fma_f16 v68, v68, v63, v73
	v_pk_fma_f16 v66, v66, v63, v70
	v_pk_fma_f16 v69, v69, v63, v74
	v_pk_fma_f16 v60, v67, v63, v60
	v_cvt_scalef32_pk_f16_fp8 v63, v56, 1.0
	v_cvt_scalef32_pk_f16_fp8 v56, v56, 1.0 op_sel:[1,0,0]
	v_pk_fma_f16 v56, v56, v36, v62
	v_cvt_scalef32_pk_f16_fp8 v62, v57, 1.0
	v_pk_fma_f16 v61, v63, v36, v61
	v_pk_fma_f16 v62, v62, v36, v64
	v_cvt_scalef32_pk_f16_fp8 v57, v57, 1.0 op_sel:[1,0,0]
	v_cvt_scalef32_pk_f16_fp8 v63, v58, 1.0
	v_cvt_scalef32_pk_f16_fp8 v58, v58, 1.0 op_sel:[1,0,0]
	v_cvt_scalef32_pk_f16_fp8 v64, v59, 1.0
	v_cvt_scalef32_pk_f16_fp8 v59, v59, 1.0 op_sel:[1,0,0]
	v_pk_fma_f16 v57, v57, v36, v65
	v_pk_fma_f16 v63, v63, v36, v68
	v_pk_fma_f16 v58, v58, v36, v66
	v_pk_fma_f16 v64, v64, v36, v69
	v_pk_fma_f16 v36, v59, v36, v60
	v_cvt_scalef32_pk_f16_fp8 v59, v52, 1.0
	v_cvt_scalef32_pk_f16_fp8 v52, v52, 1.0 op_sel:[1,0,0]
	v_pk_fma_f16 v52, v52, v37, v56
	v_cvt_scalef32_pk_f16_fp8 v56, v53, 1.0
	v_cvt_scalef32_pk_f16_fp8 v53, v53, 1.0 op_sel:[1,0,0]
	v_pk_fma_f16 v53, v53, v37, v57
	v_cvt_scalef32_pk_f16_fp8 v57, v54, 1.0
	v_cvt_scalef32_pk_f16_fp8 v54, v54, 1.0 op_sel:[1,0,0]
	v_pk_fma_f16 v54, v54, v37, v58
	v_cvt_scalef32_pk_f16_fp8 v58, v55, 1.0
	v_cvt_scalef32_pk_f16_fp8 v55, v55, 1.0 op_sel:[1,0,0]
	v_pk_fma_f16 v59, v59, v37, v61
	v_pk_fma_f16 v56, v56, v37, v62
	v_pk_fma_f16 v57, v57, v37, v63
	v_pk_fma_f16 v58, v58, v37, v64
	v_pk_fma_f16 v36, v55, v37, v36
	v_cvt_scalef32_pk_f16_fp8 v37, v48, 1.0
	v_cvt_scalef32_pk_f16_fp8 v48, v48, 1.0 op_sel:[1,0,0]
	v_pk_fma_f16 v48, v48, v38, v52
	v_cvt_scalef32_pk_f16_fp8 v52, v49, 1.0
	v_cvt_scalef32_pk_f16_fp8 v49, v49, 1.0 op_sel:[1,0,0]
	v_pk_fma_f16 v49, v49, v38, v53
	v_cvt_scalef32_pk_f16_fp8 v53, v50, 1.0
	v_cvt_scalef32_pk_f16_fp8 v50, v50, 1.0 op_sel:[1,0,0]
	v_pk_fma_f16 v50, v50, v38, v54
	v_cvt_scalef32_pk_f16_fp8 v54, v51, 1.0
	v_cvt_scalef32_pk_f16_fp8 v51, v51, 1.0 op_sel:[1,0,0]
	v_pk_fma_f16 v37, v37, v38, v59
	v_pk_fma_f16 v52, v52, v38, v56
	v_pk_fma_f16 v53, v53, v38, v57
	v_pk_fma_f16 v54, v54, v38, v58
	v_pk_fma_f16 v36, v51, v38, v36
	v_cvt_scalef32_pk_f16_fp8 v38, v44, 1.0
	v_pk_fma_f16 v37, v38, v39, v37
	v_cvt_scalef32_pk_f16_fp8 v38, v44, 1.0 op_sel:[1,0,0]
	v_cvt_scalef32_pk_f16_fp8 v44, v45, 1.0
	v_cvt_scalef32_pk_f16_fp8 v45, v45, 1.0 op_sel:[1,0,0]
	v_pk_fma_f16 v38, v38, v39, v48
	v_pk_fma_f16 v45, v45, v39, v49
	v_cvt_scalef32_pk_f16_fp8 v48, v46, 1.0
	v_cvt_scalef32_pk_f16_fp8 v46, v46, 1.0 op_sel:[1,0,0]
	v_cvt_scalef32_pk_f16_fp8 v49, v47, 1.0
	v_cvt_scalef32_pk_f16_fp8 v47, v47, 1.0 op_sel:[1,0,0]
	v_pk_fma_f16 v44, v44, v39, v52
	v_pk_fma_f16 v48, v48, v39, v53
	v_pk_fma_f16 v46, v46, v39, v50
	v_pk_fma_f16 v49, v49, v39, v54
	v_pk_fma_f16 v36, v47, v39, v36
	v_cvt_scalef32_pk_f16_fp8 v39, v40, 1.0
	v_pk_fma_f16 v37, v39, v12, v37
	v_cvt_scalef32_pk_f16_fp8 v39, v40, 1.0 op_sel:[1,0,0]
	v_pk_fma_f16 v38, v39, v12, v38
	v_cvt_scalef32_pk_f16_fp8 v39, v41, 1.0
	v_pk_fma_f16 v39, v39, v12, v44
	v_cvt_scalef32_pk_f16_fp8 v40, v41, 1.0 op_sel:[1,0,0]
	v_cvt_scalef32_pk_f16_fp8 v41, v42, 1.0
	v_cvt_scalef32_pk_f16_fp8 v42, v42, 1.0 op_sel:[1,0,0]
	v_cvt_scalef32_pk_f16_fp8 v44, v43, 1.0
	v_cvt_scalef32_pk_f16_fp8 v43, v43, 1.0 op_sel:[1,0,0]
	v_pk_fma_f16 v40, v40, v12, v45
	v_pk_fma_f16 v41, v41, v12, v48
	v_pk_fma_f16 v42, v42, v12, v46
	v_pk_fma_f16 v44, v44, v12, v49
	v_pk_fma_f16 v12, v43, v12, v36
	v_cvt_scalef32_pk_f16_fp8 v36, v32, 1.0
	v_pk_fma_f16 v36, v36, v13, v37
	v_cvt_scalef32_pk_f16_fp8 v32, v32, 1.0 op_sel:[1,0,0]
	v_cvt_scalef32_pk_f16_fp8 v37, v33, 1.0
	v_pk_fma_f16 v32, v32, v13, v38
	v_pk_fma_f16 v37, v37, v13, v39
	v_cvt_scalef32_pk_f16_fp8 v33, v33, 1.0 op_sel:[1,0,0]
	v_cvt_scalef32_pk_f16_fp8 v38, v34, 1.0
	v_cvt_scalef32_pk_f16_fp8 v34, v34, 1.0 op_sel:[1,0,0]
	v_cvt_scalef32_pk_f16_fp8 v39, v35, 1.0
	v_cvt_scalef32_pk_f16_fp8 v35, v35, 1.0 op_sel:[1,0,0]
	v_pk_fma_f16 v33, v33, v13, v40
	v_pk_fma_f16 v38, v38, v13, v41
	v_pk_fma_f16 v34, v34, v13, v42
	v_pk_fma_f16 v39, v39, v13, v44
	v_pk_fma_f16 v12, v35, v13, v12
	v_cvt_scalef32_pk_f16_fp8 v13, v28, 1.0
	v_cvt_scalef32_pk_f16_fp8 v28, v28, 1.0 op_sel:[1,0,0]
	v_pk_fma_f16 v28, v28, v14, v32
	v_cvt_scalef32_pk_f16_fp8 v32, v29, 1.0
	v_cvt_scalef32_pk_f16_fp8 v29, v29, 1.0 op_sel:[1,0,0]
	v_pk_fma_f16 v29, v29, v14, v33
	v_cvt_scalef32_pk_f16_fp8 v33, v30, 1.0
	v_cvt_scalef32_pk_f16_fp8 v30, v30, 1.0 op_sel:[1,0,0]
	v_pk_fma_f16 v30, v30, v14, v34
	v_cvt_scalef32_pk_f16_fp8 v34, v31, 1.0
	v_cvt_scalef32_pk_f16_fp8 v31, v31, 1.0 op_sel:[1,0,0]
	v_pk_fma_f16 v13, v13, v14, v36
	v_pk_fma_f16 v32, v32, v14, v37
	v_pk_fma_f16 v33, v33, v14, v38
	v_pk_fma_f16 v34, v34, v14, v39
	v_pk_fma_f16 v12, v31, v14, v12
	v_cvt_scalef32_pk_f16_fp8 v14, v24, 1.0
	v_pk_fma_f16 v13, v14, v15, v13
	v_cvt_scalef32_pk_f16_fp8 v14, v24, 1.0 op_sel:[1,0,0]
	v_cvt_scalef32_pk_f16_fp8 v24, v25, 1.0
	v_cvt_scalef32_pk_f16_fp8 v25, v25, 1.0 op_sel:[1,0,0]
	v_pk_fma_f16 v14, v14, v15, v28
	v_pk_fma_f16 v25, v25, v15, v29
	v_cvt_scalef32_pk_f16_fp8 v28, v26, 1.0
	v_cvt_scalef32_pk_f16_fp8 v26, v26, 1.0 op_sel:[1,0,0]
	v_cvt_scalef32_pk_f16_fp8 v29, v27, 1.0
	v_cvt_scalef32_pk_f16_fp8 v27, v27, 1.0 op_sel:[1,0,0]
	v_pk_fma_f16 v24, v24, v15, v32
	v_pk_fma_f16 v28, v28, v15, v33
	v_pk_fma_f16 v26, v26, v15, v30
	v_pk_fma_f16 v29, v29, v15, v34
	v_pk_fma_f16 v12, v27, v15, v12
	v_cvt_scalef32_pk_f16_fp8 v15, v20, 1.0
	v_pk_fma_f16 v13, v15, v0, v13
	v_cvt_scalef32_pk_f16_fp8 v15, v20, 1.0 op_sel:[1,0,0]
	v_pk_fma_f16 v14, v15, v0, v14
	v_cvt_scalef32_pk_f16_fp8 v15, v21, 1.0
	v_pk_fma_f16 v15, v15, v0, v24
	v_cvt_scalef32_pk_f16_fp8 v20, v21, 1.0 op_sel:[1,0,0]
	v_cvt_scalef32_pk_f16_fp8 v21, v22, 1.0
	v_cvt_scalef32_pk_f16_fp8 v22, v22, 1.0 op_sel:[1,0,0]
	v_cvt_scalef32_pk_f16_fp8 v24, v23, 1.0
	v_cvt_scalef32_pk_f16_fp8 v23, v23, 1.0 op_sel:[1,0,0]
	v_pk_fma_f16 v20, v20, v0, v25
	v_pk_fma_f16 v21, v21, v0, v28
	v_pk_fma_f16 v22, v22, v0, v26
	v_pk_fma_f16 v24, v24, v0, v29
	v_pk_fma_f16 v0, v23, v0, v12
	v_cvt_scalef32_pk_f16_fp8 v12, v16, 1.0
	v_pk_fma_f16 v12, v12, v1, v13
	v_cvt_scalef32_pk_f16_fp8 v13, v16, 1.0 op_sel:[1,0,0]
	v_pk_fma_f16 v13, v13, v1, v14
	v_cvt_scalef32_pk_f16_fp8 v14, v17, 1.0
	v_pk_fma_f16 v14, v14, v1, v15
	v_cvt_scalef32_pk_f16_fp8 v15, v17, 1.0 op_sel:[1,0,0]
	v_cvt_scalef32_pk_f16_fp8 v16, v18, 1.0
	v_cvt_scalef32_pk_f16_fp8 v17, v18, 1.0 op_sel:[1,0,0]
	v_cvt_scalef32_pk_f16_fp8 v18, v19, 1.0
	v_cvt_scalef32_pk_f16_fp8 v19, v19, 1.0 op_sel:[1,0,0]
	v_pk_fma_f16 v15, v15, v1, v20
	v_pk_fma_f16 v16, v16, v1, v21
	v_pk_fma_f16 v17, v17, v1, v22
	v_pk_fma_f16 v18, v18, v1, v24
	v_pk_fma_f16 v0, v19, v1, v0
	v_cvt_scalef32_pk_f16_fp8 v1, v4, 1.0
	v_pk_fma_f16 v1, v1, v2, v12
	v_cvt_scalef32_pk_f16_fp8 v4, v4, 1.0 op_sel:[1,0,0]
	v_cvt_scalef32_pk_f16_fp8 v12, v5, 1.0
	v_pk_fma_f16 v4, v4, v2, v13
	v_pk_fma_f16 v12, v12, v2, v14
	v_cvt_scalef32_pk_f16_fp8 v5, v5, 1.0 op_sel:[1,0,0]
	v_cvt_scalef32_pk_f16_fp8 v13, v6, 1.0
	v_cvt_scalef32_pk_f16_fp8 v6, v6, 1.0 op_sel:[1,0,0]
	v_cvt_scalef32_pk_f16_fp8 v14, v7, 1.0
	v_cvt_scalef32_pk_f16_fp8 v7, v7, 1.0 op_sel:[1,0,0]
	v_pk_fma_f16 v5, v5, v2, v15
	v_pk_fma_f16 v13, v13, v2, v16
	v_pk_fma_f16 v6, v6, v2, v17
	v_pk_fma_f16 v14, v14, v2, v18
	v_pk_fma_f16 v0, v7, v2, v0
	v_cvt_scalef32_pk_f16_fp8 v2, v8, 1.0
	v_pk_fma_f16 v1, v2, v3, v1
	v_cvt_scalef32_pk_f16_fp8 v2, v8, 1.0 op_sel:[1,0,0]
	v_cvt_scalef32_pk_f16_fp8 v7, v9, 1.0 op_sel:[1,0,0]
	v_cvt_scalef32_pk_f16_fp8 v8, v10, 1.0 op_sel:[1,0,0]
	v_pk_fma_f16 v2, v2, v3, v4
	v_cvt_scalef32_pk_f16_fp8 v4, v9, 1.0
	v_pk_fma_f16 v5, v7, v3, v5
	v_cvt_scalef32_pk_f16_fp8 v7, v10, 1.0
	v_pk_fma_f16 v6, v8, v3, v6
	v_cvt_scalef32_pk_f16_fp8 v8, v11, 1.0
	v_cvt_scalef32_pk_f16_fp8 v9, v11, 1.0 op_sel:[1,0,0]
	v_pk_fma_f16 v4, v4, v3, v12
	v_pk_fma_f16 v7, v7, v3, v13
	v_pk_fma_f16 v8, v8, v3, v14
	v_pk_fma_f16 v0, v9, v3, v0
	v_permlane32_swap_b32_e32 v1, v7
	v_permlane32_swap_b32_e32 v2, v6
	v_permlane32_swap_b32_e32 v4, v8
	v_permlane32_swap_b32_e32 v5, v0
	v_pk_add_f16 v1, v1, v7
	v_pk_add_f16 v2, v2, v6
	v_pk_add_f16 v3, v4, v8
	v_pk_add_f16 v0, v5, v0
	s_nop 0
	v_permlane16_swap_b32_e32 v1, v3
	v_permlane16_swap_b32_e32 v2, v0
	v_pk_add_f16 v1, v1, v3
	v_pk_add_f16 v0, v2, v0
	s_ashr_i32 s17, s16, 31
	v_cndmask_b32_e64 v2, v1, v0, s[2:3]
	v_cndmask_b32_e64 v0, v0, v1, s[2:3]
	s_lshl_b64 s[16:17], s[16:17], 11
	v_mov_b32_dpp v1, v2 row_ror:8 row_mask:0xf bank_mask:0xf bound_ctrl:1
	v_pk_add_f16 v1, v1, v0
	s_add_u32 s24, s14, s16
	v_cvt_f32_f16_e32 v0, v1
	v_cvt_f32_f16_sdwa v1, v1 dst_sel:DWORD dst_unused:UNUSED_PAD src0_sel:WORD_1
	s_addc_u32 s25, s15, s17
	s_lshl_b32 s16, s9, 7
	s_ashr_i32 s17, s16, 31
	v_pk_mul_f32 v[0:1], v[0:1], s[10:11] op_sel_hi:[1,0]
	s_lshl_b64 s[16:17], s[16:17], 1
	v_and_b32_sdwa v3, v0, v208 dst_sel:DWORD dst_unused:UNUSED_PAD src0_sel:WORD_1 src1_sel:DWORD
	v_and_b32_sdwa v2, v1, v208 dst_sel:DWORD dst_unused:UNUSED_PAD src0_sel:WORD_1 src1_sel:DWORD
	v_add3_u32 v0, v0, v3, s7
	s_add_u32 s16, s24, s16
	v_add3_u32 v1, v1, v2, s7
	v_lshrrev_b32_e32 v0, 16, v0
	s_addc_u32 s17, s25, s17
	v_and_or_b32 v2, v1, s11, v0
	v_lshl_add_u64 v[0:1], s[16:17], 0, v[194:195]
	s_mov_b32 s18, s27
	s_mov_b32 s23, s26
	v_lshl_add_u64 v[0:1], v[0:1], 0, v[204:205]
	s_cmp_gt_i32 s22, 7
	s_mov_b64 s[16:17], -1
	global_store_dword v[0:1], v2, off
	s_cbranch_scc1 .LBB0_621
	s_add_i32 s9, s23, s19
	s_cmpk_gt_i32 s9, 0x3fff
	s_cselect_b32 s25, s33, 0
	s_cselect_b32 s24, s6, s9
	s_add_i32 s25, s25, s18
	s_and_b64 s[16:17], s[20:21], exec
	s_cselect_b32 s9, s18, s22
	v_lshl_or_b32 v0, s9, 21, v196
	s_waitcnt vmcnt(1)
	ds_swizzle_b32 v188, v250 offset:24
	ds_swizzle_b32 v189, v251 offset:24
	ds_swizzle_b32 v190, v250 offset:56
	ds_swizzle_b32 v191, v251 offset:56
	ds_swizzle_b32 v184, v250 offset:88
	ds_swizzle_b32 v185, v251 offset:88
	ds_swizzle_b32 v186, v250 offset:120
	ds_swizzle_b32 v187, v251 offset:120
	ds_swizzle_b32 v180, v250 offset:152
	ds_swizzle_b32 v181, v251 offset:152
	ds_swizzle_b32 v182, v250 offset:184
	ds_swizzle_b32 v183, v251 offset:184
	ds_swizzle_b32 v176, v250 offset:216
	ds_swizzle_b32 v177, v251 offset:216
	ds_swizzle_b32 v178, v250 offset:248
	ds_swizzle_b32 v179, v251 offset:248
	s_waitcnt lgkmcnt(0)
	s_nop 0
	v_lshl_add_u32 v1, v188, 7, v0
	s_cselect_b32 s16, s23, s8
	v_lshl_add_u32 v2, v189, 7, v0
	global_load_dwordx4 v[76:79], v1, s[4:5]
	global_load_dwordx4 v[72:75], v2, s[4:5]
	v_lshl_add_u32 v1, v190, 7, v0
	s_ashr_i32 s17, s16, 31
	v_lshl_add_u32 v2, v191, 7, v0
	global_load_dwordx4 v[68:71], v1, s[4:5]
	global_load_dwordx4 v[64:67], v2, s[4:5]
	v_lshl_add_u32 v1, v184, 7, v0
	s_lshl_b64 s[16:17], s[16:17], 9
	v_lshl_add_u32 v2, v185, 7, v0
	global_load_dwordx4 v[56:59], v1, s[4:5]
	global_load_dwordx4 v[52:55], v2, s[4:5]
	v_lshl_add_u32 v1, v186, 7, v0
	s_cmp_lt_i32 s25, 8
	v_lshl_add_u32 v2, v187, 7, v0
	global_load_dwordx4 v[48:51], v1, s[4:5]
	global_load_dwordx4 v[44:47], v2, s[4:5]
	v_lshl_add_u32 v1, v180, 7, v0
	v_lshl_add_u64 v[60:61], v[244:245], 0, s[16:17]
	s_cselect_b32 s16, s24, s8
	v_lshl_add_u32 v2, v181, 7, v0
	global_load_dwordx4 v[40:43], v1, s[4:5]
	global_load_dwordx4 v[32:35], v2, s[4:5]
	v_lshl_add_u32 v1, v182, 7, v0
	s_ashr_i32 s17, s16, 31
	v_lshl_add_u32 v2, v183, 7, v0
	global_load_dwordx4 v[28:31], v1, s[4:5]
	global_load_dwordx4 v[24:27], v2, s[4:5]
	v_lshl_add_u32 v1, v176, 7, v0
	s_lshl_b64 s[16:17], s[16:17], 9
	v_lshl_add_u32 v2, v177, 7, v0
	global_load_dwordx4 v[20:23], v1, s[4:5]
	global_load_dwordx4 v[16:19], v2, s[4:5]
	v_lshl_add_u32 v1, v178, 7, v0
	v_lshl_add_u32 v0, v179, 7, v0
	v_lshl_add_u64 v[140:141], v[246:247], 0, s[16:17]
	global_load_dwordx4 v[4:7], v1, s[4:5]
	global_load_dwordx4 v[8:11], v0, s[4:5]
	s_nop 0
	ds_swizzle_b32 v172, v248 offset:24
	ds_swizzle_b32 v173, v249 offset:24
	ds_swizzle_b32 v174, v248 offset:56
	ds_swizzle_b32 v175, v249 offset:56
	ds_swizzle_b32 v148, v248 offset:88
	ds_swizzle_b32 v149, v249 offset:88
	ds_swizzle_b32 v150, v248 offset:120
	ds_swizzle_b32 v151, v249 offset:120
	ds_swizzle_b32 v116, v248 offset:152
	ds_swizzle_b32 v117, v249 offset:152
	ds_swizzle_b32 v118, v248 offset:184
	ds_swizzle_b32 v119, v249 offset:184
	ds_swizzle_b32 v84, v248 offset:216
	ds_swizzle_b32 v85, v249 offset:216
	ds_swizzle_b32 v86, v248 offset:248
	ds_swizzle_b32 v87, v249 offset:248
	global_load_dwordx2 v[248:249], v[60:61], off
	s_nop 0
	global_load_dwordx2 v[250:251], v[140:141], off
	s_waitcnt lgkmcnt(0)
	s_nop 0
	v_cvt_scalef32_pk_f16_fp8 v176, v168, 1.0
	v_cvt_scalef32_pk_f16_fp8 v168, v168, 1.0 op_sel:[1,0,0]
	v_cvt_scalef32_pk_f16_fp8 v177, v169, 1.0
	v_cvt_scalef32_pk_f16_fp8 v169, v169, 1.0 op_sel:[1,0,0]
	v_cvt_scalef32_pk_f16_fp8 v178, v170, 1.0
	v_cvt_scalef32_pk_f16_fp8 v170, v170, 1.0 op_sel:[1,0,0]
	v_cvt_scalef32_pk_f16_fp8 v179, v171, 1.0
	v_cvt_scalef32_pk_f16_fp8 v171, v171, 1.0 op_sel:[1,0,0]
	v_pk_fma_f16 v176, v176, v172, 0
	v_pk_fma_f16 v168, v168, v172, 0
	v_pk_fma_f16 v177, v177, v172, 0
	v_pk_fma_f16 v169, v169, v172, 0
	v_pk_fma_f16 v178, v178, v172, 0
	v_pk_fma_f16 v170, v170, v172, 0
	v_pk_fma_f16 v179, v179, v172, 0
	v_pk_fma_f16 v171, v171, v172, 0
	v_cvt_scalef32_pk_f16_fp8 v172, v164, 1.0
	v_cvt_scalef32_pk_f16_fp8 v164, v164, 1.0 op_sel:[1,0,0]
	v_pk_fma_f16 v164, v164, v173, v168
	v_cvt_scalef32_pk_f16_fp8 v168, v165, 1.0
	v_cvt_scalef32_pk_f16_fp8 v165, v165, 1.0 op_sel:[1,0,0]
	v_pk_fma_f16 v165, v165, v173, v169
	v_cvt_scalef32_pk_f16_fp8 v169, v166, 1.0
	v_cvt_scalef32_pk_f16_fp8 v166, v166, 1.0 op_sel:[1,0,0]
	v_pk_fma_f16 v166, v166, v173, v170
	v_cvt_scalef32_pk_f16_fp8 v170, v167, 1.0
	v_cvt_scalef32_pk_f16_fp8 v167, v167, 1.0 op_sel:[1,0,0]
	v_pk_fma_f16 v167, v167, v173, v171
	v_cvt_scalef32_pk_f16_fp8 v171, v160, 1.0
	v_cvt_scalef32_pk_f16_fp8 v160, v160, 1.0 op_sel:[1,0,0]
	v_pk_fma_f16 v160, v160, v174, v164
	v_cvt_scalef32_pk_f16_fp8 v164, v161, 1.0
	v_cvt_scalef32_pk_f16_fp8 v161, v161, 1.0 op_sel:[1,0,0]
	v_pk_fma_f16 v161, v161, v174, v165
	v_cvt_scalef32_pk_f16_fp8 v165, v162, 1.0
	v_cvt_scalef32_pk_f16_fp8 v162, v162, 1.0 op_sel:[1,0,0]
	v_pk_fma_f16 v162, v162, v174, v166
	v_cvt_scalef32_pk_f16_fp8 v166, v163, 1.0
	v_cvt_scalef32_pk_f16_fp8 v163, v163, 1.0 op_sel:[1,0,0]
	v_pk_fma_f16 v163, v163, v174, v167
	v_cvt_scalef32_pk_f16_fp8 v167, v156, 1.0
	v_cvt_scalef32_pk_f16_fp8 v156, v156, 1.0 op_sel:[1,0,0]
	v_pk_fma_f16 v156, v156, v175, v160
	v_cvt_scalef32_pk_f16_fp8 v160, v157, 1.0
	v_cvt_scalef32_pk_f16_fp8 v157, v157, 1.0 op_sel:[1,0,0]
	v_pk_fma_f16 v157, v157, v175, v161
	v_cvt_scalef32_pk_f16_fp8 v161, v158, 1.0
	v_cvt_scalef32_pk_f16_fp8 v158, v158, 1.0 op_sel:[1,0,0]
	v_pk_fma_f16 v158, v158, v175, v162
	v_cvt_scalef32_pk_f16_fp8 v162, v159, 1.0
	v_cvt_scalef32_pk_f16_fp8 v159, v159, 1.0 op_sel:[1,0,0]
	v_pk_fma_f16 v159, v159, v175, v163
	v_cvt_scalef32_pk_f16_fp8 v163, v152, 1.0
	v_cvt_scalef32_pk_f16_fp8 v152, v152, 1.0 op_sel:[1,0,0]
	v_pk_fma_f16 v172, v172, v173, v176
	v_pk_fma_f16 v168, v168, v173, v177
	v_pk_fma_f16 v169, v169, v173, v178
	v_pk_fma_f16 v170, v170, v173, v179
	v_pk_fma_f16 v152, v152, v148, v156
	v_cvt_scalef32_pk_f16_fp8 v156, v153, 1.0
	v_cvt_scalef32_pk_f16_fp8 v153, v153, 1.0 op_sel:[1,0,0]
	v_pk_fma_f16 v171, v171, v174, v172
	v_pk_fma_f16 v164, v164, v174, v168
	v_pk_fma_f16 v165, v165, v174, v169
	v_pk_fma_f16 v166, v166, v174, v170
	v_pk_fma_f16 v153, v153, v148, v157
	v_cvt_scalef32_pk_f16_fp8 v157, v154, 1.0
	v_cvt_scalef32_pk_f16_fp8 v154, v154, 1.0 op_sel:[1,0,0]
	v_pk_fma_f16 v167, v167, v175, v171
	v_pk_fma_f16 v160, v160, v175, v164
	v_pk_fma_f16 v161, v161, v175, v165
	v_pk_fma_f16 v162, v162, v175, v166
	v_pk_fma_f16 v154, v154, v148, v158
	v_cvt_scalef32_pk_f16_fp8 v158, v155, 1.0
	v_cvt_scalef32_pk_f16_fp8 v155, v155, 1.0 op_sel:[1,0,0]
	v_pk_fma_f16 v163, v163, v148, v167
	v_pk_fma_f16 v156, v156, v148, v160
	v_pk_fma_f16 v157, v157, v148, v161
	v_pk_fma_f16 v158, v158, v148, v162
	v_pk_fma_f16 v148, v155, v148, v159
	v_cvt_scalef32_pk_f16_fp8 v155, v144, 1.0
	v_cvt_scalef32_pk_f16_fp8 v144, v144, 1.0 op_sel:[1,0,0]
	v_pk_fma_f16 v144, v144, v149, v152
	v_cvt_scalef32_pk_f16_fp8 v152, v145, 1.0
	v_cvt_scalef32_pk_f16_fp8 v145, v145, 1.0 op_sel:[1,0,0]
	v_pk_fma_f16 v145, v145, v149, v153
	v_cvt_scalef32_pk_f16_fp8 v153, v146, 1.0
	v_cvt_scalef32_pk_f16_fp8 v146, v146, 1.0 op_sel:[1,0,0]
	v_pk_fma_f16 v146, v146, v149, v154
	v_cvt_scalef32_pk_f16_fp8 v154, v147, 1.0
	v_cvt_scalef32_pk_f16_fp8 v147, v147, 1.0 op_sel:[1,0,0]
	v_pk_fma_f16 v147, v147, v149, v148
	v_cvt_scalef32_pk_f16_fp8 v148, v136, 1.0
	v_cvt_scalef32_pk_f16_fp8 v136, v136, 1.0 op_sel:[1,0,0]
	v_pk_fma_f16 v136, v136, v150, v144
	v_cvt_scalef32_pk_f16_fp8 v144, v137, 1.0
	v_cvt_scalef32_pk_f16_fp8 v137, v137, 1.0 op_sel:[1,0,0]
	v_pk_fma_f16 v137, v137, v150, v145
	v_cvt_scalef32_pk_f16_fp8 v145, v138, 1.0
	v_cvt_scalef32_pk_f16_fp8 v138, v138, 1.0 op_sel:[1,0,0]
	v_pk_fma_f16 v138, v138, v150, v146
	v_cvt_scalef32_pk_f16_fp8 v146, v139, 1.0
	v_cvt_scalef32_pk_f16_fp8 v139, v139, 1.0 op_sel:[1,0,0]
	v_pk_fma_f16 v139, v139, v150, v147
	v_cvt_scalef32_pk_f16_fp8 v147, v128, 1.0
	v_cvt_scalef32_pk_f16_fp8 v128, v128, 1.0 op_sel:[1,0,0]
	v_pk_fma_f16 v128, v128, v151, v136
	v_cvt_scalef32_pk_f16_fp8 v136, v129, 1.0
	v_cvt_scalef32_pk_f16_fp8 v129, v129, 1.0 op_sel:[1,0,0]
	v_pk_fma_f16 v129, v129, v151, v137
	v_cvt_scalef32_pk_f16_fp8 v137, v130, 1.0
	v_cvt_scalef32_pk_f16_fp8 v130, v130, 1.0 op_sel:[1,0,0]
	v_pk_fma_f16 v130, v130, v151, v138
	v_cvt_scalef32_pk_f16_fp8 v138, v131, 1.0
	v_cvt_scalef32_pk_f16_fp8 v131, v131, 1.0 op_sel:[1,0,0]
	v_pk_fma_f16 v131, v131, v151, v139
	v_cvt_scalef32_pk_f16_fp8 v139, v124, 1.0
	v_cvt_scalef32_pk_f16_fp8 v124, v124, 1.0 op_sel:[1,0,0]
	v_pk_fma_f16 v155, v155, v149, v163
	v_pk_fma_f16 v152, v152, v149, v156
	v_pk_fma_f16 v153, v153, v149, v157
	v_pk_fma_f16 v154, v154, v149, v158
	v_pk_fma_f16 v124, v124, v116, v128
	v_cvt_scalef32_pk_f16_fp8 v128, v125, 1.0
	v_cvt_scalef32_pk_f16_fp8 v125, v125, 1.0 op_sel:[1,0,0]
	v_pk_fma_f16 v148, v148, v150, v155
	v_pk_fma_f16 v144, v144, v150, v152
	v_pk_fma_f16 v145, v145, v150, v153
	v_pk_fma_f16 v146, v146, v150, v154
	v_pk_fma_f16 v125, v125, v116, v129
	v_cvt_scalef32_pk_f16_fp8 v129, v126, 1.0
	v_cvt_scalef32_pk_f16_fp8 v126, v126, 1.0 op_sel:[1,0,0]
	v_pk_fma_f16 v147, v147, v151, v148
	v_pk_fma_f16 v136, v136, v151, v144
	v_pk_fma_f16 v137, v137, v151, v145
	v_pk_fma_f16 v138, v138, v151, v146
	v_pk_fma_f16 v126, v126, v116, v130
	v_cvt_scalef32_pk_f16_fp8 v130, v127, 1.0
	v_cvt_scalef32_pk_f16_fp8 v127, v127, 1.0 op_sel:[1,0,0]
	v_pk_fma_f16 v139, v139, v116, v147
	v_pk_fma_f16 v128, v128, v116, v136
	v_pk_fma_f16 v129, v129, v116, v137
	v_pk_fma_f16 v130, v130, v116, v138
	v_pk_fma_f16 v116, v127, v116, v131
	v_cvt_scalef32_pk_f16_fp8 v127, v120, 1.0
	v_cvt_scalef32_pk_f16_fp8 v120, v120, 1.0 op_sel:[1,0,0]
	v_pk_fma_f16 v120, v120, v117, v124
	v_cvt_scalef32_pk_f16_fp8 v124, v121, 1.0
	v_cvt_scalef32_pk_f16_fp8 v121, v121, 1.0 op_sel:[1,0,0]
	v_pk_fma_f16 v121, v121, v117, v125
	v_cvt_scalef32_pk_f16_fp8 v125, v122, 1.0
	v_cvt_scalef32_pk_f16_fp8 v122, v122, 1.0 op_sel:[1,0,0]
	v_pk_fma_f16 v122, v122, v117, v126
	v_cvt_scalef32_pk_f16_fp8 v126, v123, 1.0
	v_cvt_scalef32_pk_f16_fp8 v123, v123, 1.0 op_sel:[1,0,0]
	v_pk_fma_f16 v127, v127, v117, v139
	v_pk_fma_f16 v124, v124, v117, v128
	v_pk_fma_f16 v125, v125, v117, v129
	v_pk_fma_f16 v126, v126, v117, v130
	v_pk_fma_f16 v116, v123, v117, v116
	v_cvt_scalef32_pk_f16_fp8 v117, v112, 1.0
	v_cvt_scalef32_pk_f16_fp8 v112, v112, 1.0 op_sel:[1,0,0]
	v_pk_fma_f16 v112, v112, v118, v120
	v_cvt_scalef32_pk_f16_fp8 v120, v113, 1.0
	v_cvt_scalef32_pk_f16_fp8 v113, v113, 1.0 op_sel:[1,0,0]
	v_pk_fma_f16 v113, v113, v118, v121
	v_cvt_scalef32_pk_f16_fp8 v121, v114, 1.0
	v_cvt_scalef32_pk_f16_fp8 v114, v114, 1.0 op_sel:[1,0,0]
	v_pk_fma_f16 v114, v114, v118, v122
	v_cvt_scalef32_pk_f16_fp8 v122, v115, 1.0
	v_cvt_scalef32_pk_f16_fp8 v115, v115, 1.0 op_sel:[1,0,0]
	v_pk_fma_f16 v115, v115, v118, v116
	v_cvt_scalef32_pk_f16_fp8 v116, v104, 1.0
	v_cvt_scalef32_pk_f16_fp8 v104, v104, 1.0 op_sel:[1,0,0]
	v_pk_fma_f16 v104, v104, v119, v112
	v_cvt_scalef32_pk_f16_fp8 v112, v105, 1.0
	v_cvt_scalef32_pk_f16_fp8 v105, v105, 1.0 op_sel:[1,0,0]
	v_pk_fma_f16 v105, v105, v119, v113
	v_cvt_scalef32_pk_f16_fp8 v113, v106, 1.0
	v_cvt_scalef32_pk_f16_fp8 v106, v106, 1.0 op_sel:[1,0,0]
	v_pk_fma_f16 v106, v106, v119, v114
	v_cvt_scalef32_pk_f16_fp8 v114, v107, 1.0
	v_cvt_scalef32_pk_f16_fp8 v107, v107, 1.0 op_sel:[1,0,0]
	v_pk_fma_f16 v107, v107, v119, v115
	v_cvt_scalef32_pk_f16_fp8 v115, v96, 1.0
	v_cvt_scalef32_pk_f16_fp8 v96, v96, 1.0 op_sel:[1,0,0]
	v_pk_fma_f16 v96, v96, v84, v104
	v_cvt_scalef32_pk_f16_fp8 v104, v97, 1.0
	v_cvt_scalef32_pk_f16_fp8 v97, v97, 1.0 op_sel:[1,0,0]
	v_pk_fma_f16 v117, v117, v118, v127
	v_pk_fma_f16 v120, v120, v118, v124
	v_pk_fma_f16 v121, v121, v118, v125
	v_pk_fma_f16 v122, v122, v118, v126
	v_pk_fma_f16 v97, v97, v84, v105
	v_cvt_scalef32_pk_f16_fp8 v105, v98, 1.0
	v_cvt_scalef32_pk_f16_fp8 v98, v98, 1.0 op_sel:[1,0,0]
	v_pk_fma_f16 v116, v116, v119, v117
	v_pk_fma_f16 v112, v112, v119, v120
	v_pk_fma_f16 v113, v113, v119, v121
	v_pk_fma_f16 v114, v114, v119, v122
	v_pk_fma_f16 v98, v98, v84, v106
	v_cvt_scalef32_pk_f16_fp8 v106, v99, 1.0
	v_cvt_scalef32_pk_f16_fp8 v99, v99, 1.0 op_sel:[1,0,0]
	v_pk_fma_f16 v115, v115, v84, v116
	v_pk_fma_f16 v104, v104, v84, v112
	v_pk_fma_f16 v105, v105, v84, v113
	v_pk_fma_f16 v106, v106, v84, v114
	v_pk_fma_f16 v84, v99, v84, v107
	v_cvt_scalef32_pk_f16_fp8 v99, v92, 1.0
	v_cvt_scalef32_pk_f16_fp8 v92, v92, 1.0 op_sel:[1,0,0]
	v_pk_fma_f16 v92, v92, v85, v96
	v_cvt_scalef32_pk_f16_fp8 v96, v93, 1.0
	v_cvt_scalef32_pk_f16_fp8 v93, v93, 1.0 op_sel:[1,0,0]
	v_pk_fma_f16 v93, v93, v85, v97
	v_cvt_scalef32_pk_f16_fp8 v97, v94, 1.0
	v_cvt_scalef32_pk_f16_fp8 v94, v94, 1.0 op_sel:[1,0,0]
	v_pk_fma_f16 v94, v94, v85, v98
	v_cvt_scalef32_pk_f16_fp8 v98, v95, 1.0
	v_cvt_scalef32_pk_f16_fp8 v95, v95, 1.0 op_sel:[1,0,0]
	v_pk_fma_f16 v99, v99, v85, v115
	v_pk_fma_f16 v96, v96, v85, v104
	v_pk_fma_f16 v97, v97, v85, v105
	v_pk_fma_f16 v98, v98, v85, v106
	v_pk_fma_f16 v84, v95, v85, v84
	v_cvt_scalef32_pk_f16_fp8 v85, v88, 1.0
	v_cvt_scalef32_pk_f16_fp8 v88, v88, 1.0 op_sel:[1,0,0]
	v_pk_fma_f16 v88, v88, v86, v92
	v_cvt_scalef32_pk_f16_fp8 v92, v89, 1.0
	v_cvt_scalef32_pk_f16_fp8 v89, v89, 1.0 op_sel:[1,0,0]
	v_pk_fma_f16 v89, v89, v86, v93
	v_cvt_scalef32_pk_f16_fp8 v93, v90, 1.0
	v_cvt_scalef32_pk_f16_fp8 v90, v90, 1.0 op_sel:[1,0,0]
	v_pk_fma_f16 v90, v90, v86, v94
	v_cvt_scalef32_pk_f16_fp8 v94, v91, 1.0
	v_cvt_scalef32_pk_f16_fp8 v91, v91, 1.0 op_sel:[1,0,0]
	v_pk_fma_f16 v85, v85, v86, v99
	v_pk_fma_f16 v92, v92, v86, v96
	v_pk_fma_f16 v93, v93, v86, v97
	v_pk_fma_f16 v94, v94, v86, v98
	v_pk_fma_f16 v84, v91, v86, v84
	v_cvt_scalef32_pk_f16_fp8 v86, v80, 1.0
	v_pk_fma_f16 v85, v86, v87, v85
	v_cvt_scalef32_pk_f16_fp8 v80, v80, 1.0 op_sel:[1,0,0]
	v_cvt_scalef32_pk_f16_fp8 v86, v81, 1.0
	v_cvt_scalef32_pk_f16_fp8 v81, v81, 1.0 op_sel:[1,0,0]
	v_pk_fma_f16 v80, v80, v87, v88
	v_pk_fma_f16 v81, v81, v87, v89
	v_cvt_scalef32_pk_f16_fp8 v88, v82, 1.0
	v_cvt_scalef32_pk_f16_fp8 v82, v82, 1.0 op_sel:[1,0,0]
	v_cvt_scalef32_pk_f16_fp8 v89, v83, 1.0
	v_cvt_scalef32_pk_f16_fp8 v83, v83, 1.0 op_sel:[1,0,0]
	v_pk_fma_f16 v86, v86, v87, v92
	v_pk_fma_f16 v88, v88, v87, v93
	v_pk_fma_f16 v82, v82, v87, v90
	v_pk_fma_f16 v89, v89, v87, v94
	v_pk_fma_f16 v83, v83, v87, v84
	v_permlane32_swap_b32_e32 v85, v88
	v_permlane32_swap_b32_e32 v80, v82
	v_permlane32_swap_b32_e32 v86, v89
	v_permlane32_swap_b32_e32 v81, v83
	v_pk_add_f16 v84, v85, v88
	v_pk_add_f16 v80, v80, v82
	v_pk_add_f16 v82, v86, v89
	v_pk_add_f16 v81, v81, v83
	s_nop 0
	v_permlane16_swap_b32_e32 v84, v82
	v_permlane16_swap_b32_e32 v80, v81
	v_pk_add_f16 v82, v84, v82
	v_pk_add_f16 v80, v80, v81
	s_ashr_i32 s9, s8, 31
	v_cndmask_b32_e64 v81, v82, v80, s[2:3]
	v_cndmask_b32_e64 v80, v80, v82, s[2:3]
	s_lshl_b64 s[8:9], s[8:9], 11
	v_mov_b32_dpp v81, v81 row_ror:8 row_mask:0xf bank_mask:0xf bound_ctrl:1
	v_pk_add_f16 v81, v81, v80
	s_add_u32 s16, s14, s8
	v_cvt_f32_f16_e32 v80, v81
	v_cvt_f32_f16_sdwa v81, v81 dst_sel:DWORD dst_unused:UNUSED_PAD src0_sel:WORD_1
	s_addc_u32 s17, s15, s9
	s_lshl_b32 s8, s22, 7
	s_ashr_i32 s9, s8, 31
	v_pk_mul_f32 v[80:81], v[80:81], s[10:11] op_sel_hi:[1,0]
	s_lshl_b64 s[8:9], s[8:9], 1
	v_and_b32_sdwa v83, v80, v208 dst_sel:DWORD dst_unused:UNUSED_PAD src0_sel:WORD_1 src1_sel:DWORD
	v_and_b32_sdwa v82, v81, v208 dst_sel:DWORD dst_unused:UNUSED_PAD src0_sel:WORD_1 src1_sel:DWORD
	v_add3_u32 v80, v80, v83, s7
	s_add_u32 s8, s16, s8
	v_add3_u32 v81, v81, v82, s7
	v_lshrrev_b32_e32 v80, 16, v80
	s_addc_u32 s9, s17, s9
	v_and_or_b32 v82, v81, s11, v80
	v_lshl_add_u64 v[80:81], s[8:9], 0, v[194:195]
	s_add_i32 s8, s24, s19
	s_cmpk_gt_i32 s8, 0x3fff
	s_cselect_b32 s26, s6, s8
	s_cselect_b32 s8, s33, 0
	s_add_i32 s27, s8, s25
	v_mov_b32_e32 v203, v195
	s_cmp_gt_i32 s18, 7
	v_lshl_add_u64 v[80:81], v[80:81], 0, v[202:203]
	s_cselect_b64 s[16:17], -1, 0
	s_mov_b32 s22, s25
	s_mov_b32 s8, s24
	global_store_dword v[80:81], v82, off
	s_branch .LBB0_621
